# P13 EpiZ first half: all eight y-tile loads issued up front as global loads, single wait, store-draining waits removed
# speedup vs baseline: 1.0005x; 1.0005x over previous
.LBB0_1634:
	v_mov_b32_e32 v123, v186
	v_mov_b32_e32 v122, v187
	s_nop 0
	v_lshlrev_b32_e32 v122, 3, v122
	v_add_u32_e32 v124, s69, v122
	v_ashrrev_i32_e32 v125, 31, v124
	v_lshl_add_u64 v[184:185], v[124:125], 2, s[54:55]
	v_add_u32_e32 v124, s68, v123
	v_ashrrev_i32_e32 v125, 31, v124
	global_load_dwordx4 v[138:141], v[184:185], off
	global_load_dwordx4 v[134:137], v[184:185], off offset:16
	v_lshlrev_b64 v[124:125], 11, v[124:125]
	v_lshl_add_u64 v[124:125], s[52:53], 0, v[124:125]
	v_ashrrev_i32_e32 v123, 31, v122
	v_lshl_add_u64 v[124:125], v[124:125], 0, s[18:19]
	v_lshl_add_u64 v[182:183], v[122:123], 1, v[124:125]
	global_load_dwordx4 v[192:195], v[182:183], off
	v_add_co_u32_e32 v180, vcc, s71, v182
	s_nop 1
	v_addc_co_u32_e32 v181, vcc, 0, v183, vcc
	global_load_dwordx4 v[196:199], v[180:181], off
	v_add_co_u32_e32 v178, vcc, s26, v182
	s_nop 1
	v_addc_co_u32_e32 v179, vcc, 0, v183, vcc
	global_load_dwordx4 v[158:161], v[178:179], off
	v_add_co_u32_e32 v176, vcc, s70, v182
	s_nop 1
	v_addc_co_u32_e32 v177, vcc, 0, v183, vcc
	global_load_dwordx4 v[154:157], v[176:177], off
	v_add_co_u32_e32 v174, vcc, s74, v182
	s_nop 1
	v_addc_co_u32_e32 v175, vcc, 0, v183, vcc
	global_load_dwordx4 v[150:153], v[174:175], off
	v_add_co_u32_e32 v172, vcc, s75, v182
	s_nop 1
	v_addc_co_u32_e32 v173, vcc, 0, v183, vcc
	global_load_dwordx4 v[146:149], v[172:173], off
	v_add_co_u32_e32 v170, vcc, s76, v182
	s_nop 1
	v_addc_co_u32_e32 v171, vcc, 0, v183, vcc
	global_load_dwordx4 v[142:145], v[170:171], off
	v_add_co_u32_e32 v168, vcc, s77, v182
	s_nop 1
	v_addc_co_u32_e32 v169, vcc, 0, v183, vcc
	global_load_dwordx4 v[122:125], v[168:169], off
	s_waitcnt vmcnt(0)
	v_pk_add_f32 v[132:133], v[132:133], v[140:141]
	v_pk_add_f32 v[130:131], v[130:131], v[138:139]
	s_nop 0
	v_pk_add_f32 v[200:201], v[128:129], v[136:137]
	s_nop 0
	v_pk_add_f32 v[126:127], v[126:127], v[134:135]
	s_nop 0
	v_mul_f32_e32 v128, 0xbfb8aa3b, v130
	v_mul_f32_e32 v129, 0xbfb8aa3b, v131
	v_mul_f32_e32 v202, 0xbfb8aa3b, v132
	v_mul_f32_e32 v203, 0xbfb8aa3b, v133
	v_mul_f32_e32 v204, 0xbfb8aa3b, v126
	v_exp_f32_e32 v128, v128
	v_exp_f32_e32 v129, v129
	v_exp_f32_e32 v202, v202
	v_mul_f32_e32 v205, 0xbfb8aa3b, v127
	v_exp_f32_e32 v203, v203
	v_exp_f32_e32 v204, v204
	v_exp_f32_e32 v205, v205
	v_lshlrev_b32_e32 v206, 16, v192
	v_and_b32_e32 v192, 0xffff0000, v192
	v_lshlrev_b32_e32 v208, 16, v194
	v_and_b32_e32 v194, 0xffff0000, v194
	v_lshlrev_b32_e32 v207, 16, v193
	v_and_b32_e32 v193, 0xffff0000, v193
	v_mul_f32_e32 v131, v131, v192
	v_mul_f32_e32 v192, v127, v194
	v_add_f32_e32 v127, 1.0, v128
	v_add_f32_e32 v128, 1.0, v129
	v_add_f32_e32 v129, 1.0, v202
	v_mul_f32_e32 v133, v133, v193
	v_add_f32_e32 v193, 1.0, v203
	v_add_f32_e32 v194, 1.0, v204
	v_rcp_f32_e32 v127, v127
	v_rcp_f32_e32 v129, v129
	v_add_f32_e32 v202, 1.0, v205
	v_rcp_f32_e32 v128, v128
	v_rcp_f32_e32 v193, v193
	v_rcp_f32_e32 v194, v194
	v_rcp_f32_e32 v202, v202
	v_mul_f32_e32 v130, v130, v206
	v_mul_f32_e32 v132, v132, v207
	v_mul_f32_e32 v126, v126, v208
	v_mul_f32_e32 v127, v130, v127
	v_mul_f32_e32 v129, v132, v129
	v_mul_f32_e32 v128, v131, v128
	v_mul_f32_e32 v130, v133, v193
	v_mul_f32_e32 v131, v126, v194
	v_cvt_pk_bf16_f32 v126, v127, v128
	v_cvt_pk_bf16_f32 v127, v129, v130
	v_mul_f32_e32 v129, 0xbfb8aa3b, v200
	v_mul_f32_e32 v128, v192, v202
	v_exp_f32_e32 v129, v129
	v_cvt_pk_bf16_f32 v128, v131, v128
	v_mul_f32_e32 v131, 0xbfb8aa3b, v201
	v_exp_f32_e32 v131, v131
	v_add_f32_e32 v129, 1.0, v129
	v_rcp_f32_e32 v129, v129
	v_lshlrev_b32_e32 v130, 16, v195
	v_add_f32_e32 v131, 1.0, v131
	v_rcp_f32_e32 v131, v131
	v_mul_f32_e32 v130, v200, v130
	v_mul_f32_e32 v129, v130, v129
	v_and_b32_e32 v130, 0xffff0000, v195
	v_mul_f32_e32 v130, v201, v130
	v_pk_add_f32 v[118:119], v[118:119], v[138:139]
	v_mul_f32_e32 v130, v130, v131
	v_cvt_pk_bf16_f32 v129, v129, v130
	global_store_dwordx4 v[182:183], v[126:129], off
	v_pk_add_f32 v[120:121], v[120:121], v[140:141]
	v_pk_add_f32 v[110:111], v[110:111], v[138:139]
	v_pk_add_f32 v[126:127], v[116:117], v[136:137]
	v_pk_add_f32 v[116:117], v[114:115], v[134:135]
	v_mul_f32_e32 v114, 0xbfb8aa3b, v118
	v_exp_f32_e32 v114, v114
	v_mul_f32_e32 v128, 0xbfb8aa3b, v119
	v_exp_f32_e32 v128, v128
	v_lshlrev_b32_e32 v115, 16, v196
	v_add_f32_e32 v114, 1.0, v114
	v_rcp_f32_e32 v114, v114
	v_mul_f32_e32 v115, v118, v115
	v_add_f32_e32 v118, 1.0, v128
	v_rcp_f32_e32 v118, v118
	v_mul_f32_e32 v114, v114, v115
	v_and_b32_e32 v115, 0xffff0000, v196
	v_mul_f32_e32 v115, v119, v115
	v_mul_f32_e32 v115, v118, v115
	v_cvt_pk_bf16_f32 v114, v114, v115
	v_mul_f32_e32 v115, 0xbfb8aa3b, v120
	v_exp_f32_e32 v115, v115
	v_mul_f32_e32 v119, 0xbfb8aa3b, v121
	v_exp_f32_e32 v119, v119
	v_lshlrev_b32_e32 v118, 16, v197
	v_add_f32_e32 v115, 1.0, v115
	v_rcp_f32_e32 v115, v115
	v_add_f32_e32 v119, 1.0, v119
	v_rcp_f32_e32 v119, v119
	v_mul_f32_e32 v118, v120, v118
	v_mul_f32_e32 v115, v115, v118
	v_and_b32_e32 v118, 0xffff0000, v197
	v_mul_f32_e32 v118, v121, v118
	v_mul_f32_e32 v118, v119, v118
	v_cvt_pk_bf16_f32 v115, v115, v118
	v_mul_f32_e32 v118, 0xbfb8aa3b, v116
	v_exp_f32_e32 v118, v118
	v_mul_f32_e32 v120, 0xbfb8aa3b, v117
	v_exp_f32_e32 v120, v120
	v_lshlrev_b32_e32 v119, 16, v198
	v_add_f32_e32 v118, 1.0, v118
	v_rcp_f32_e32 v118, v118
	v_mul_f32_e32 v116, v116, v119
	v_add_f32_e32 v119, 1.0, v120
	v_rcp_f32_e32 v119, v119
	v_mul_f32_e32 v116, v116, v118
	v_and_b32_e32 v118, 0xffff0000, v198
	v_mul_f32_e32 v117, v117, v118
	v_mul_f32_e32 v117, v117, v119
	v_cvt_pk_bf16_f32 v116, v116, v117
	v_mul_f32_e32 v117, 0xbfb8aa3b, v126
	v_exp_f32_e32 v117, v117
	v_mul_f32_e32 v119, 0xbfb8aa3b, v127
	v_exp_f32_e32 v119, v119
	v_lshlrev_b32_e32 v118, 16, v199
	v_add_f32_e32 v117, 1.0, v117
	v_rcp_f32_e32 v117, v117
	v_add_f32_e32 v119, 1.0, v119
	v_rcp_f32_e32 v119, v119
	v_mul_f32_e32 v118, v126, v118
	v_mul_f32_e32 v117, v118, v117
	v_and_b32_e32 v118, 0xffff0000, v199
	v_mul_f32_e32 v118, v127, v118
	v_mul_f32_e32 v118, v118, v119
	v_cvt_pk_bf16_f32 v117, v117, v118
	global_store_dwordx4 v[180:181], v[114:117], off
	v_pk_add_f32 v[112:113], v[112:113], v[140:141]
	v_pk_add_f32 v[102:103], v[102:103], v[138:139]
	v_pk_add_f32 v[114:115], v[108:109], v[136:137]
	v_pk_add_f32 v[108:109], v[106:107], v[134:135]
	v_mul_f32_e32 v106, 0xbfb8aa3b, v110
	v_exp_f32_e32 v106, v106
	v_mul_f32_e32 v116, 0xbfb8aa3b, v111
	v_exp_f32_e32 v116, v116
	v_lshlrev_b32_e32 v107, 16, v158
	v_add_f32_e32 v106, 1.0, v106
	v_rcp_f32_e32 v106, v106
	v_mul_f32_e32 v107, v110, v107
	v_add_f32_e32 v110, 1.0, v116
	v_rcp_f32_e32 v110, v110
	v_mul_f32_e32 v106, v106, v107
	v_and_b32_e32 v107, 0xffff0000, v158
	v_mul_f32_e32 v107, v111, v107
	v_mul_f32_e32 v107, v110, v107
	v_cvt_pk_bf16_f32 v106, v106, v107
	v_mul_f32_e32 v107, 0xbfb8aa3b, v112
	v_exp_f32_e32 v107, v107
	v_mul_f32_e32 v111, 0xbfb8aa3b, v113
	v_exp_f32_e32 v111, v111
	v_lshlrev_b32_e32 v110, 16, v159
	v_add_f32_e32 v107, 1.0, v107
	v_rcp_f32_e32 v107, v107
	v_add_f32_e32 v111, 1.0, v111
	v_rcp_f32_e32 v111, v111
	v_mul_f32_e32 v110, v112, v110
	v_mul_f32_e32 v107, v107, v110
	v_and_b32_e32 v110, 0xffff0000, v159
	v_mul_f32_e32 v110, v113, v110
	v_mul_f32_e32 v110, v111, v110
	v_cvt_pk_bf16_f32 v107, v107, v110
	v_mul_f32_e32 v110, 0xbfb8aa3b, v108
	v_exp_f32_e32 v110, v110
	v_mul_f32_e32 v112, 0xbfb8aa3b, v109
	v_exp_f32_e32 v112, v112
	v_lshlrev_b32_e32 v111, 16, v160
	v_add_f32_e32 v110, 1.0, v110
	v_rcp_f32_e32 v110, v110
	v_mul_f32_e32 v108, v108, v111
	v_add_f32_e32 v111, 1.0, v112
	v_rcp_f32_e32 v111, v111
	v_mul_f32_e32 v108, v110, v108
	v_and_b32_e32 v110, 0xffff0000, v160
	v_mul_f32_e32 v109, v109, v110
	v_mul_f32_e32 v109, v111, v109
	v_cvt_pk_bf16_f32 v108, v108, v109
	v_mul_f32_e32 v109, 0xbfb8aa3b, v114
	v_exp_f32_e32 v109, v109
	v_mul_f32_e32 v111, 0xbfb8aa3b, v115
	v_exp_f32_e32 v111, v111
	v_lshlrev_b32_e32 v110, 16, v161
	v_add_f32_e32 v109, 1.0, v109
	v_rcp_f32_e32 v109, v109
	v_add_f32_e32 v111, 1.0, v111
	v_rcp_f32_e32 v111, v111
	v_mul_f32_e32 v110, v114, v110
	v_mul_f32_e32 v109, v109, v110
	v_and_b32_e32 v110, 0xffff0000, v161
	v_mul_f32_e32 v110, v115, v110
	v_mul_f32_e32 v110, v111, v110
	v_cvt_pk_bf16_f32 v109, v109, v110
	global_store_dwordx4 v[178:179], v[106:109], off
	v_pk_add_f32 v[104:105], v[104:105], v[140:141]
	v_pk_add_f32 v[94:95], v[94:95], v[138:139]
	v_pk_add_f32 v[106:107], v[100:101], v[136:137]
	v_pk_add_f32 v[100:101], v[98:99], v[134:135]
	v_mul_f32_e32 v98, 0xbfb8aa3b, v102
	v_exp_f32_e32 v98, v98
	v_mul_f32_e32 v108, 0xbfb8aa3b, v103
	v_exp_f32_e32 v108, v108
	v_lshlrev_b32_e32 v99, 16, v154
	v_add_f32_e32 v98, 1.0, v98
	v_rcp_f32_e32 v98, v98
	v_mul_f32_e32 v99, v102, v99
	v_add_f32_e32 v102, 1.0, v108
	v_rcp_f32_e32 v102, v102
	v_mul_f32_e32 v98, v98, v99
	v_and_b32_e32 v99, 0xffff0000, v154
	v_mul_f32_e32 v99, v103, v99
	v_mul_f32_e32 v99, v102, v99
	v_cvt_pk_bf16_f32 v98, v98, v99
	v_mul_f32_e32 v99, 0xbfb8aa3b, v104
	v_exp_f32_e32 v99, v99
	v_mul_f32_e32 v103, 0xbfb8aa3b, v105
	v_exp_f32_e32 v103, v103
	v_lshlrev_b32_e32 v102, 16, v155
	v_add_f32_e32 v99, 1.0, v99
	v_rcp_f32_e32 v99, v99
	v_add_f32_e32 v103, 1.0, v103
	v_rcp_f32_e32 v103, v103
	v_mul_f32_e32 v102, v104, v102
	v_mul_f32_e32 v99, v99, v102
	v_and_b32_e32 v102, 0xffff0000, v155
	v_mul_f32_e32 v102, v105, v102
	v_mul_f32_e32 v102, v103, v102
	v_cvt_pk_bf16_f32 v99, v99, v102
	v_mul_f32_e32 v102, 0xbfb8aa3b, v100
	v_exp_f32_e32 v102, v102
	v_mul_f32_e32 v104, 0xbfb8aa3b, v101
	v_exp_f32_e32 v104, v104
	v_lshlrev_b32_e32 v103, 16, v156
	v_add_f32_e32 v102, 1.0, v102
	v_rcp_f32_e32 v102, v102
	v_mul_f32_e32 v100, v100, v103
	v_add_f32_e32 v103, 1.0, v104
	v_rcp_f32_e32 v103, v103
	v_mul_f32_e32 v100, v102, v100
	v_and_b32_e32 v102, 0xffff0000, v156
	v_mul_f32_e32 v101, v101, v102
	v_mul_f32_e32 v101, v103, v101
	v_cvt_pk_bf16_f32 v100, v100, v101
	v_mul_f32_e32 v101, 0xbfb8aa3b, v106
	v_exp_f32_e32 v101, v101
	v_mul_f32_e32 v103, 0xbfb8aa3b, v107
	v_exp_f32_e32 v103, v103
	v_lshlrev_b32_e32 v102, 16, v157
	v_add_f32_e32 v101, 1.0, v101
	v_rcp_f32_e32 v101, v101
	v_add_f32_e32 v103, 1.0, v103
	v_rcp_f32_e32 v103, v103
	v_mul_f32_e32 v102, v106, v102
	v_mul_f32_e32 v101, v101, v102
	v_and_b32_e32 v102, 0xffff0000, v157
	v_mul_f32_e32 v102, v107, v102
	v_mul_f32_e32 v102, v103, v102
	v_cvt_pk_bf16_f32 v101, v101, v102
	global_store_dwordx4 v[176:177], v[98:101], off
	v_pk_add_f32 v[96:97], v[96:97], v[140:141]
	v_pk_add_f32 v[86:87], v[86:87], v[138:139]
	v_pk_add_f32 v[98:99], v[92:93], v[136:137]
	v_pk_add_f32 v[92:93], v[90:91], v[134:135]
	v_mul_f32_e32 v90, 0xbfb8aa3b, v94
	v_exp_f32_e32 v90, v90
	v_mul_f32_e32 v100, 0xbfb8aa3b, v95
	v_exp_f32_e32 v100, v100
	v_lshlrev_b32_e32 v91, 16, v150
	v_add_f32_e32 v90, 1.0, v90
	v_rcp_f32_e32 v90, v90
	v_mul_f32_e32 v91, v94, v91
	v_add_f32_e32 v94, 1.0, v100
	v_rcp_f32_e32 v94, v94
	v_mul_f32_e32 v90, v90, v91
	v_and_b32_e32 v91, 0xffff0000, v150
	v_mul_f32_e32 v91, v95, v91
	v_mul_f32_e32 v91, v94, v91
	v_cvt_pk_bf16_f32 v90, v90, v91
	v_mul_f32_e32 v91, 0xbfb8aa3b, v96
	v_exp_f32_e32 v91, v91
	v_mul_f32_e32 v95, 0xbfb8aa3b, v97
	v_exp_f32_e32 v95, v95
	v_lshlrev_b32_e32 v94, 16, v151
	v_add_f32_e32 v91, 1.0, v91
	v_rcp_f32_e32 v91, v91
	v_add_f32_e32 v95, 1.0, v95
	v_rcp_f32_e32 v95, v95
	v_mul_f32_e32 v94, v96, v94
	v_mul_f32_e32 v91, v91, v94
	v_and_b32_e32 v94, 0xffff0000, v151
	v_mul_f32_e32 v94, v97, v94
	v_mul_f32_e32 v94, v95, v94
	v_cvt_pk_bf16_f32 v91, v91, v94
	v_mul_f32_e32 v94, 0xbfb8aa3b, v92
	v_exp_f32_e32 v94, v94
	v_mul_f32_e32 v96, 0xbfb8aa3b, v93
	v_exp_f32_e32 v96, v96
	v_lshlrev_b32_e32 v95, 16, v152
	v_add_f32_e32 v94, 1.0, v94
	v_rcp_f32_e32 v94, v94
	v_mul_f32_e32 v92, v92, v95
	v_add_f32_e32 v95, 1.0, v96
	v_rcp_f32_e32 v95, v95
	v_mul_f32_e32 v92, v94, v92
	v_and_b32_e32 v94, 0xffff0000, v152
	v_mul_f32_e32 v93, v93, v94
	v_mul_f32_e32 v93, v95, v93
	v_cvt_pk_bf16_f32 v92, v92, v93
	v_mul_f32_e32 v93, 0xbfb8aa3b, v98
	v_exp_f32_e32 v93, v93
	v_mul_f32_e32 v95, 0xbfb8aa3b, v99
	v_exp_f32_e32 v95, v95
	v_lshlrev_b32_e32 v94, 16, v153
	v_add_f32_e32 v93, 1.0, v93
	v_rcp_f32_e32 v93, v93
	v_add_f32_e32 v95, 1.0, v95
	v_rcp_f32_e32 v95, v95
	v_mul_f32_e32 v94, v98, v94
	v_mul_f32_e32 v93, v93, v94
	v_and_b32_e32 v94, 0xffff0000, v153
	v_mul_f32_e32 v94, v99, v94
	v_mul_f32_e32 v94, v95, v94
	v_cvt_pk_bf16_f32 v93, v93, v94
	global_store_dwordx4 v[174:175], v[90:93], off
	v_pk_add_f32 v[88:89], v[88:89], v[140:141]
	v_pk_add_f32 v[78:79], v[78:79], v[138:139]
	v_pk_add_f32 v[90:91], v[84:85], v[136:137]
	v_pk_add_f32 v[84:85], v[82:83], v[134:135]
	v_mul_f32_e32 v82, 0xbfb8aa3b, v86
	v_exp_f32_e32 v82, v82
	v_mul_f32_e32 v92, 0xbfb8aa3b, v87
	v_exp_f32_e32 v92, v92
	v_lshlrev_b32_e32 v83, 16, v146
	v_add_f32_e32 v82, 1.0, v82
	v_rcp_f32_e32 v82, v82
	v_mul_f32_e32 v83, v86, v83
	v_add_f32_e32 v86, 1.0, v92
	v_rcp_f32_e32 v86, v86
	v_mul_f32_e32 v82, v82, v83
	v_and_b32_e32 v83, 0xffff0000, v146
	v_mul_f32_e32 v83, v87, v83
	v_mul_f32_e32 v83, v86, v83
	v_cvt_pk_bf16_f32 v82, v82, v83
	v_mul_f32_e32 v83, 0xbfb8aa3b, v88
	v_exp_f32_e32 v83, v83
	v_mul_f32_e32 v87, 0xbfb8aa3b, v89
	v_exp_f32_e32 v87, v87
	v_lshlrev_b32_e32 v86, 16, v147
	v_add_f32_e32 v83, 1.0, v83
	v_rcp_f32_e32 v83, v83
	v_add_f32_e32 v87, 1.0, v87
	v_rcp_f32_e32 v87, v87
	v_mul_f32_e32 v86, v88, v86
	v_mul_f32_e32 v83, v83, v86
	v_and_b32_e32 v86, 0xffff0000, v147
	v_mul_f32_e32 v86, v89, v86
	v_mul_f32_e32 v86, v87, v86
	v_cvt_pk_bf16_f32 v83, v83, v86
	v_mul_f32_e32 v86, 0xbfb8aa3b, v84
	v_exp_f32_e32 v86, v86
	v_mul_f32_e32 v88, 0xbfb8aa3b, v85
	v_exp_f32_e32 v88, v88
	v_lshlrev_b32_e32 v87, 16, v148
	v_add_f32_e32 v86, 1.0, v86
	v_rcp_f32_e32 v86, v86
	v_mul_f32_e32 v84, v84, v87
	v_add_f32_e32 v87, 1.0, v88
	v_rcp_f32_e32 v87, v87
	v_mul_f32_e32 v84, v86, v84
	v_and_b32_e32 v86, 0xffff0000, v148
	v_mul_f32_e32 v85, v85, v86
	v_mul_f32_e32 v85, v87, v85
	v_cvt_pk_bf16_f32 v84, v84, v85
	v_mul_f32_e32 v85, 0xbfb8aa3b, v90
	v_exp_f32_e32 v85, v85
	v_mul_f32_e32 v87, 0xbfb8aa3b, v91
	v_exp_f32_e32 v87, v87
	v_lshlrev_b32_e32 v86, 16, v149
	v_add_f32_e32 v85, 1.0, v85
	v_rcp_f32_e32 v85, v85
	v_add_f32_e32 v87, 1.0, v87
	v_rcp_f32_e32 v87, v87
	v_mul_f32_e32 v86, v90, v86
	v_mul_f32_e32 v85, v85, v86
	v_and_b32_e32 v86, 0xffff0000, v149
	v_mul_f32_e32 v86, v91, v86
	v_mul_f32_e32 v86, v87, v86
	v_cvt_pk_bf16_f32 v85, v85, v86
	global_store_dwordx4 v[172:173], v[82:85], off
	v_pk_add_f32 v[80:81], v[80:81], v[140:141]
	v_pk_add_f32 v[70:71], v[70:71], v[138:139]
	v_pk_add_f32 v[82:83], v[76:77], v[136:137]
	v_pk_add_f32 v[76:77], v[74:75], v[134:135]
	v_mul_f32_e32 v74, 0xbfb8aa3b, v78
	v_exp_f32_e32 v74, v74
	v_mul_f32_e32 v84, 0xbfb8aa3b, v79
	v_exp_f32_e32 v84, v84
	v_lshlrev_b32_e32 v75, 16, v142
	v_add_f32_e32 v74, 1.0, v74
	v_rcp_f32_e32 v74, v74
	v_mul_f32_e32 v75, v78, v75
	v_add_f32_e32 v78, 1.0, v84
	v_rcp_f32_e32 v78, v78
	v_mul_f32_e32 v74, v74, v75
	v_and_b32_e32 v75, 0xffff0000, v142
	v_mul_f32_e32 v75, v79, v75
	v_mul_f32_e32 v75, v78, v75
	v_cvt_pk_bf16_f32 v74, v74, v75
	v_mul_f32_e32 v75, 0xbfb8aa3b, v80
	v_exp_f32_e32 v75, v75
	v_mul_f32_e32 v79, 0xbfb8aa3b, v81
	v_exp_f32_e32 v79, v79
	v_lshlrev_b32_e32 v78, 16, v143
	v_add_f32_e32 v75, 1.0, v75
	v_rcp_f32_e32 v75, v75
	v_add_f32_e32 v79, 1.0, v79
	v_rcp_f32_e32 v79, v79
	v_mul_f32_e32 v78, v80, v78
	v_mul_f32_e32 v75, v75, v78
	v_and_b32_e32 v78, 0xffff0000, v143
	v_mul_f32_e32 v78, v81, v78
	v_mul_f32_e32 v78, v79, v78
	v_cvt_pk_bf16_f32 v75, v75, v78
	v_mul_f32_e32 v78, 0xbfb8aa3b, v76
	v_exp_f32_e32 v78, v78
	v_mul_f32_e32 v80, 0xbfb8aa3b, v77
	v_exp_f32_e32 v80, v80
	v_lshlrev_b32_e32 v79, 16, v144
	v_add_f32_e32 v78, 1.0, v78
	v_rcp_f32_e32 v78, v78
	v_mul_f32_e32 v76, v76, v79
	v_add_f32_e32 v79, 1.0, v80
	v_rcp_f32_e32 v79, v79
	v_mul_f32_e32 v76, v78, v76
	v_and_b32_e32 v78, 0xffff0000, v144
	v_mul_f32_e32 v77, v77, v78
	v_mul_f32_e32 v77, v79, v77
	v_cvt_pk_bf16_f32 v76, v76, v77
	v_mul_f32_e32 v77, 0xbfb8aa3b, v82
	v_exp_f32_e32 v77, v77
	v_mul_f32_e32 v79, 0xbfb8aa3b, v83
	v_exp_f32_e32 v79, v79
	v_lshlrev_b32_e32 v78, 16, v145
	v_add_f32_e32 v77, 1.0, v77
	v_rcp_f32_e32 v77, v77
	v_add_f32_e32 v79, 1.0, v79
	v_rcp_f32_e32 v79, v79
	v_mul_f32_e32 v78, v82, v78
	v_mul_f32_e32 v77, v77, v78
	v_and_b32_e32 v78, 0xffff0000, v145
	v_mul_f32_e32 v78, v83, v78
	v_mul_f32_e32 v78, v79, v78
	v_cvt_pk_bf16_f32 v77, v77, v78
	global_store_dwordx4 v[170:171], v[74:77], off
	v_pk_add_f32 v[72:73], v[72:73], v[140:141]
	s_andn2_b64 vcc, exec, s[46:47]
	v_pk_add_f32 v[74:75], v[68:69], v[136:137]
	v_pk_add_f32 v[68:69], v[66:67], v[134:135]
	v_mul_f32_e32 v66, 0xbfb8aa3b, v70
	v_exp_f32_e32 v66, v66
	v_mul_f32_e32 v76, 0xbfb8aa3b, v71
	v_exp_f32_e32 v76, v76
	v_lshlrev_b32_e32 v67, 16, v122
	v_add_f32_e32 v66, 1.0, v66
	v_rcp_f32_e32 v66, v66
	v_mul_f32_e32 v67, v70, v67
	v_add_f32_e32 v70, 1.0, v76
	v_rcp_f32_e32 v70, v70
	v_mul_f32_e32 v66, v66, v67
	v_and_b32_e32 v67, 0xffff0000, v122
	v_mul_f32_e32 v67, v71, v67
	v_mul_f32_e32 v67, v70, v67
	v_cvt_pk_bf16_f32 v66, v66, v67
	v_mul_f32_e32 v67, 0xbfb8aa3b, v72
	v_exp_f32_e32 v67, v67
	v_mul_f32_e32 v71, 0xbfb8aa3b, v73
	v_exp_f32_e32 v71, v71
	v_lshlrev_b32_e32 v70, 16, v123
	v_add_f32_e32 v67, 1.0, v67
	v_rcp_f32_e32 v67, v67
	v_add_f32_e32 v71, 1.0, v71
	v_rcp_f32_e32 v71, v71
	v_mul_f32_e32 v70, v72, v70
	v_mul_f32_e32 v67, v67, v70
	v_and_b32_e32 v70, 0xffff0000, v123
	v_mul_f32_e32 v70, v73, v70
	v_mul_f32_e32 v70, v71, v70
	v_cvt_pk_bf16_f32 v67, v67, v70
	v_mul_f32_e32 v70, 0xbfb8aa3b, v68
	v_exp_f32_e32 v70, v70
	v_mul_f32_e32 v72, 0xbfb8aa3b, v69
	v_exp_f32_e32 v72, v72
	v_lshlrev_b32_e32 v71, 16, v124
	v_add_f32_e32 v70, 1.0, v70
	v_rcp_f32_e32 v70, v70
	v_mul_f32_e32 v68, v68, v71
	v_add_f32_e32 v71, 1.0, v72
	v_rcp_f32_e32 v71, v71
	v_mul_f32_e32 v68, v70, v68
	v_and_b32_e32 v70, 0xffff0000, v124
	v_mul_f32_e32 v69, v69, v70
	v_mul_f32_e32 v69, v71, v69
	v_cvt_pk_bf16_f32 v68, v68, v69
	v_mul_f32_e32 v69, 0xbfb8aa3b, v74
	v_exp_f32_e32 v69, v69
	v_mul_f32_e32 v71, 0xbfb8aa3b, v75
	v_exp_f32_e32 v71, v71
	v_lshlrev_b32_e32 v70, 16, v125
	v_add_f32_e32 v69, 1.0, v69
	v_rcp_f32_e32 v69, v69
	v_add_f32_e32 v71, 1.0, v71
	v_rcp_f32_e32 v71, v71
	v_mul_f32_e32 v70, v74, v70
	v_mul_f32_e32 v69, v69, v70
	v_and_b32_e32 v70, 0xffff0000, v125
	v_mul_f32_e32 v70, v75, v70
	v_mul_f32_e32 v70, v71, v70
	v_cvt_pk_bf16_f32 v69, v69, v70
	global_store_dwordx4 v[168:169], v[66:69], off
	global_load_dwordx4 v[74:77], v[184:185], off offset:512
	global_load_dwordx4 v[70:73], v[184:185], off offset:528
	global_load_dwordx4 v[98:101], v[182:183], off offset:256
	global_load_dwordx4 v[102:105], v[180:181], off offset:256
	global_load_dwordx4 v[94:97], v[178:179], off offset:256
	global_load_dwordx4 v[90:93], v[176:177], off offset:256
	global_load_dwordx4 v[86:89], v[174:175], off offset:256
	global_load_dwordx4 v[82:85], v[172:173], off offset:256
	global_load_dwordx4 v[78:81], v[170:171], off offset:256
	global_load_dwordx4 v[66:69], v[168:169], off offset:256
	s_mov_b64 s[46:47], -1
	s_waitcnt vmcnt(0)
	v_pk_add_f32 v[62:63], v[62:63], v[74:75]
	v_pk_add_f32 v[106:107], v[60:61], v[72:73]
	v_pk_add_f32 v[60:61], v[58:59], v[70:71]
	v_mul_f32_e32 v58, 0xbfb8aa3b, v62
	v_exp_f32_e32 v58, v58
	v_mul_f32_e32 v108, 0xbfb8aa3b, v63
	v_exp_f32_e32 v108, v108
	s_waitcnt lgkmcnt(0)
	v_lshlrev_b32_e32 v59, 16, v98
	v_add_f32_e32 v58, 1.0, v58
	v_rcp_f32_e32 v58, v58
	v_mul_f32_e32 v59, v62, v59
	v_add_f32_e32 v62, 1.0, v108
	v_rcp_f32_e32 v62, v62
	v_mul_f32_e32 v58, v59, v58
	v_and_b32_e32 v59, 0xffff0000, v98
	v_mul_f32_e32 v59, v63, v59
	v_pk_add_f32 v[64:65], v[64:65], v[76:77]
	v_mul_f32_e32 v59, v59, v62
	v_cvt_pk_bf16_f32 v58, v58, v59
	v_mul_f32_e32 v59, 0xbfb8aa3b, v64
	v_exp_f32_e32 v59, v59
	v_mul_f32_e32 v63, 0xbfb8aa3b, v65
	v_exp_f32_e32 v63, v63
	v_lshlrev_b32_e32 v62, 16, v99
	v_add_f32_e32 v59, 1.0, v59
	v_rcp_f32_e32 v59, v59
	v_add_f32_e32 v63, 1.0, v63
	v_rcp_f32_e32 v63, v63
	v_mul_f32_e32 v62, v64, v62
	v_mul_f32_e32 v59, v62, v59
	v_and_b32_e32 v62, 0xffff0000, v99
	v_mul_f32_e32 v62, v65, v62
	v_mul_f32_e32 v62, v62, v63
	v_cvt_pk_bf16_f32 v59, v59, v62
	v_mul_f32_e32 v62, 0xbfb8aa3b, v60
	v_exp_f32_e32 v62, v62
	v_mul_f32_e32 v64, 0xbfb8aa3b, v61
	v_exp_f32_e32 v64, v64
	v_lshlrev_b32_e32 v63, 16, v100
	v_add_f32_e32 v62, 1.0, v62
	v_rcp_f32_e32 v62, v62
	v_mul_f32_e32 v60, v60, v63
	v_add_f32_e32 v63, 1.0, v64
	v_rcp_f32_e32 v63, v63
	v_mul_f32_e32 v60, v60, v62
	v_and_b32_e32 v62, 0xffff0000, v100
	v_mul_f32_e32 v61, v61, v62
	v_mul_f32_e32 v61, v61, v63
	v_cvt_pk_bf16_f32 v60, v60, v61
	v_mul_f32_e32 v61, 0xbfb8aa3b, v106
	v_exp_f32_e32 v61, v61
	v_mul_f32_e32 v63, 0xbfb8aa3b, v107
	v_exp_f32_e32 v63, v63
	v_lshlrev_b32_e32 v62, 16, v101
	v_add_f32_e32 v61, 1.0, v61
	v_rcp_f32_e32 v61, v61
	v_add_f32_e32 v63, 1.0, v63
	v_rcp_f32_e32 v63, v63
	v_mul_f32_e32 v62, v106, v62
	v_mul_f32_e32 v61, v62, v61
	v_and_b32_e32 v62, 0xffff0000, v101
	v_mul_f32_e32 v62, v107, v62
	v_pk_add_f32 v[54:55], v[54:55], v[74:75]
	v_mul_f32_e32 v62, v62, v63
	v_cvt_pk_bf16_f32 v61, v61, v62
	global_store_dwordx4 v[182:183], v[58:61], off offset:256
	v_pk_add_f32 v[56:57], v[56:57], v[76:77]
	v_pk_add_f32 v[46:47], v[46:47], v[74:75]
	v_pk_add_f32 v[58:59], v[52:53], v[72:73]
	v_pk_add_f32 v[52:53], v[50:51], v[70:71]
	v_mul_f32_e32 v50, 0xbfb8aa3b, v54
	v_exp_f32_e32 v50, v50
	v_mul_f32_e32 v60, 0xbfb8aa3b, v55
	v_exp_f32_e32 v60, v60
	v_lshlrev_b32_e32 v51, 16, v102
	v_add_f32_e32 v50, 1.0, v50
	v_rcp_f32_e32 v50, v50
	v_mul_f32_e32 v51, v54, v51
	v_add_f32_e32 v54, 1.0, v60
	v_rcp_f32_e32 v54, v54
	v_mul_f32_e32 v50, v50, v51
	v_and_b32_e32 v51, 0xffff0000, v102
	v_mul_f32_e32 v51, v55, v51
	v_mul_f32_e32 v51, v54, v51
	v_cvt_pk_bf16_f32 v50, v50, v51
	v_mul_f32_e32 v51, 0xbfb8aa3b, v56
	v_exp_f32_e32 v51, v51
	v_mul_f32_e32 v55, 0xbfb8aa3b, v57
	v_exp_f32_e32 v55, v55
	v_lshlrev_b32_e32 v54, 16, v103
	v_add_f32_e32 v51, 1.0, v51
	v_rcp_f32_e32 v51, v51
	v_add_f32_e32 v55, 1.0, v55
	v_rcp_f32_e32 v55, v55
	v_mul_f32_e32 v54, v56, v54
	v_mul_f32_e32 v51, v51, v54
	v_and_b32_e32 v54, 0xffff0000, v103
	v_mul_f32_e32 v54, v57, v54
	v_mul_f32_e32 v54, v55, v54
	v_cvt_pk_bf16_f32 v51, v51, v54
	v_mul_f32_e32 v54, 0xbfb8aa3b, v52
	v_exp_f32_e32 v54, v54
	v_mul_f32_e32 v56, 0xbfb8aa3b, v53
	v_exp_f32_e32 v56, v56
	v_lshlrev_b32_e32 v55, 16, v104
	v_add_f32_e32 v54, 1.0, v54
	v_rcp_f32_e32 v54, v54
	v_mul_f32_e32 v52, v52, v55
	v_add_f32_e32 v55, 1.0, v56
	v_rcp_f32_e32 v55, v55
	v_mul_f32_e32 v52, v52, v54
	v_and_b32_e32 v54, 0xffff0000, v104
	v_mul_f32_e32 v53, v53, v54
	v_mul_f32_e32 v53, v53, v55
	v_cvt_pk_bf16_f32 v52, v52, v53
	v_mul_f32_e32 v53, 0xbfb8aa3b, v58
	v_exp_f32_e32 v53, v53
	v_mul_f32_e32 v55, 0xbfb8aa3b, v59
	v_exp_f32_e32 v55, v55
	v_lshlrev_b32_e32 v54, 16, v105
	v_add_f32_e32 v53, 1.0, v53
	v_rcp_f32_e32 v53, v53
	v_add_f32_e32 v55, 1.0, v55
	v_rcp_f32_e32 v55, v55
	v_mul_f32_e32 v54, v58, v54
	v_mul_f32_e32 v53, v54, v53
	v_and_b32_e32 v54, 0xffff0000, v105
	v_mul_f32_e32 v54, v59, v54
	v_mul_f32_e32 v54, v54, v55
	v_cvt_pk_bf16_f32 v53, v53, v54
	global_store_dwordx4 v[180:181], v[50:53], off offset:256
	v_pk_add_f32 v[48:49], v[48:49], v[76:77]
	v_pk_add_f32 v[38:39], v[38:39], v[74:75]
	v_pk_add_f32 v[50:51], v[44:45], v[72:73]
	v_pk_add_f32 v[44:45], v[42:43], v[70:71]
	v_mul_f32_e32 v42, 0xbfb8aa3b, v46
	v_exp_f32_e32 v42, v42
	v_mul_f32_e32 v52, 0xbfb8aa3b, v47
	v_exp_f32_e32 v52, v52
	v_lshlrev_b32_e32 v43, 16, v94
	v_add_f32_e32 v42, 1.0, v42
	v_rcp_f32_e32 v42, v42
	v_mul_f32_e32 v43, v46, v43
	v_add_f32_e32 v46, 1.0, v52
	v_rcp_f32_e32 v46, v46
	v_mul_f32_e32 v42, v42, v43
	v_and_b32_e32 v43, 0xffff0000, v94
	v_mul_f32_e32 v43, v47, v43
	v_mul_f32_e32 v43, v46, v43
	v_cvt_pk_bf16_f32 v42, v42, v43
	v_mul_f32_e32 v43, 0xbfb8aa3b, v48
	v_exp_f32_e32 v43, v43
	v_mul_f32_e32 v47, 0xbfb8aa3b, v49
	v_exp_f32_e32 v47, v47
	v_lshlrev_b32_e32 v46, 16, v95
	v_add_f32_e32 v43, 1.0, v43
	v_rcp_f32_e32 v43, v43
	v_add_f32_e32 v47, 1.0, v47
	v_rcp_f32_e32 v47, v47
	v_mul_f32_e32 v46, v48, v46
	v_mul_f32_e32 v43, v43, v46
	v_and_b32_e32 v46, 0xffff0000, v95
	v_mul_f32_e32 v46, v49, v46
	v_mul_f32_e32 v46, v47, v46
	v_cvt_pk_bf16_f32 v43, v43, v46
	v_mul_f32_e32 v46, 0xbfb8aa3b, v44
	v_exp_f32_e32 v46, v46
	v_mul_f32_e32 v48, 0xbfb8aa3b, v45
	v_exp_f32_e32 v48, v48
	v_lshlrev_b32_e32 v47, 16, v96
	v_add_f32_e32 v46, 1.0, v46
	v_rcp_f32_e32 v46, v46
	v_mul_f32_e32 v44, v44, v47
	v_add_f32_e32 v47, 1.0, v48
	v_rcp_f32_e32 v47, v47
	v_mul_f32_e32 v44, v46, v44
	v_and_b32_e32 v46, 0xffff0000, v96
	v_mul_f32_e32 v45, v45, v46
	v_mul_f32_e32 v45, v47, v45
	v_cvt_pk_bf16_f32 v44, v44, v45
	v_mul_f32_e32 v45, 0xbfb8aa3b, v50
	v_exp_f32_e32 v45, v45
	v_mul_f32_e32 v47, 0xbfb8aa3b, v51
	v_exp_f32_e32 v47, v47
	v_lshlrev_b32_e32 v46, 16, v97
	v_add_f32_e32 v45, 1.0, v45
	v_rcp_f32_e32 v45, v45
	v_add_f32_e32 v47, 1.0, v47
	v_rcp_f32_e32 v47, v47
	v_mul_f32_e32 v46, v50, v46
	v_mul_f32_e32 v45, v45, v46
	v_and_b32_e32 v46, 0xffff0000, v97
	v_mul_f32_e32 v46, v51, v46
	v_mul_f32_e32 v46, v47, v46
	v_cvt_pk_bf16_f32 v45, v45, v46
	global_store_dwordx4 v[178:179], v[42:45], off offset:256
	v_pk_add_f32 v[40:41], v[40:41], v[76:77]
	v_pk_add_f32 v[30:31], v[30:31], v[74:75]
	v_pk_add_f32 v[42:43], v[36:37], v[72:73]
	v_pk_add_f32 v[36:37], v[34:35], v[70:71]
	v_mul_f32_e32 v34, 0xbfb8aa3b, v38
	v_exp_f32_e32 v34, v34
	v_mul_f32_e32 v44, 0xbfb8aa3b, v39
	v_exp_f32_e32 v44, v44
	v_lshlrev_b32_e32 v35, 16, v90
	v_add_f32_e32 v34, 1.0, v34
	v_rcp_f32_e32 v34, v34
	v_mul_f32_e32 v35, v38, v35
	v_add_f32_e32 v38, 1.0, v44
	v_rcp_f32_e32 v38, v38
	v_mul_f32_e32 v34, v34, v35
	v_and_b32_e32 v35, 0xffff0000, v90
	v_mul_f32_e32 v35, v39, v35
	v_mul_f32_e32 v35, v38, v35
	v_cvt_pk_bf16_f32 v34, v34, v35
	v_mul_f32_e32 v35, 0xbfb8aa3b, v40
	v_exp_f32_e32 v35, v35
	v_mul_f32_e32 v39, 0xbfb8aa3b, v41
	v_exp_f32_e32 v39, v39
	v_lshlrev_b32_e32 v38, 16, v91
	v_add_f32_e32 v35, 1.0, v35
	v_rcp_f32_e32 v35, v35
	v_add_f32_e32 v39, 1.0, v39
	v_rcp_f32_e32 v39, v39
	v_mul_f32_e32 v38, v40, v38
	v_mul_f32_e32 v35, v35, v38
	v_and_b32_e32 v38, 0xffff0000, v91
	v_mul_f32_e32 v38, v41, v38
	v_mul_f32_e32 v38, v39, v38
	v_cvt_pk_bf16_f32 v35, v35, v38
	v_mul_f32_e32 v38, 0xbfb8aa3b, v36
	v_exp_f32_e32 v38, v38
	v_mul_f32_e32 v40, 0xbfb8aa3b, v37
	v_exp_f32_e32 v40, v40
	v_lshlrev_b32_e32 v39, 16, v92
	v_add_f32_e32 v38, 1.0, v38
	v_rcp_f32_e32 v38, v38
	v_mul_f32_e32 v36, v36, v39
	v_add_f32_e32 v39, 1.0, v40
	v_rcp_f32_e32 v39, v39
	v_mul_f32_e32 v36, v38, v36
	v_and_b32_e32 v38, 0xffff0000, v92
	v_mul_f32_e32 v37, v37, v38
	v_mul_f32_e32 v37, v39, v37
	v_cvt_pk_bf16_f32 v36, v36, v37
	v_mul_f32_e32 v37, 0xbfb8aa3b, v42
	v_exp_f32_e32 v37, v37
	v_mul_f32_e32 v39, 0xbfb8aa3b, v43
	v_exp_f32_e32 v39, v39
	v_lshlrev_b32_e32 v38, 16, v93
	v_add_f32_e32 v37, 1.0, v37
	v_rcp_f32_e32 v37, v37
	v_add_f32_e32 v39, 1.0, v39
	v_rcp_f32_e32 v39, v39
	v_mul_f32_e32 v38, v42, v38
	v_mul_f32_e32 v37, v37, v38
	v_and_b32_e32 v38, 0xffff0000, v93
	v_mul_f32_e32 v38, v43, v38
	v_mul_f32_e32 v38, v39, v38
	v_cvt_pk_bf16_f32 v37, v37, v38
	global_store_dwordx4 v[176:177], v[34:37], off offset:256
	v_pk_add_f32 v[32:33], v[32:33], v[76:77]
	v_pk_add_f32 v[22:23], v[22:23], v[74:75]
	v_pk_add_f32 v[34:35], v[28:29], v[72:73]
	v_pk_add_f32 v[28:29], v[26:27], v[70:71]
	v_mul_f32_e32 v26, 0xbfb8aa3b, v30
	v_exp_f32_e32 v26, v26
	v_mul_f32_e32 v36, 0xbfb8aa3b, v31
	v_exp_f32_e32 v36, v36
	v_lshlrev_b32_e32 v27, 16, v86
	v_add_f32_e32 v26, 1.0, v26
	v_rcp_f32_e32 v26, v26
	v_mul_f32_e32 v27, v30, v27
	v_add_f32_e32 v30, 1.0, v36
	v_rcp_f32_e32 v30, v30
	v_mul_f32_e32 v26, v26, v27
	v_and_b32_e32 v27, 0xffff0000, v86
	v_mul_f32_e32 v27, v31, v27
	v_mul_f32_e32 v27, v30, v27
	v_cvt_pk_bf16_f32 v26, v26, v27
	v_mul_f32_e32 v27, 0xbfb8aa3b, v32
	v_exp_f32_e32 v27, v27
	v_mul_f32_e32 v31, 0xbfb8aa3b, v33
	v_exp_f32_e32 v31, v31
	v_lshlrev_b32_e32 v30, 16, v87
	v_add_f32_e32 v27, 1.0, v27
	v_rcp_f32_e32 v27, v27
	v_add_f32_e32 v31, 1.0, v31
	v_rcp_f32_e32 v31, v31
	v_mul_f32_e32 v30, v32, v30
	v_mul_f32_e32 v27, v27, v30
	v_and_b32_e32 v30, 0xffff0000, v87
	v_mul_f32_e32 v30, v33, v30
	v_mul_f32_e32 v30, v31, v30
	v_cvt_pk_bf16_f32 v27, v27, v30
	v_mul_f32_e32 v30, 0xbfb8aa3b, v28
	v_exp_f32_e32 v30, v30
	v_mul_f32_e32 v32, 0xbfb8aa3b, v29
	v_exp_f32_e32 v32, v32
	v_lshlrev_b32_e32 v31, 16, v88
	v_add_f32_e32 v30, 1.0, v30
	v_rcp_f32_e32 v30, v30
	v_mul_f32_e32 v28, v28, v31
	v_add_f32_e32 v31, 1.0, v32
	v_rcp_f32_e32 v31, v31
	v_mul_f32_e32 v28, v30, v28
	v_and_b32_e32 v30, 0xffff0000, v88
	v_mul_f32_e32 v29, v29, v30
	v_mul_f32_e32 v29, v31, v29
	v_cvt_pk_bf16_f32 v28, v28, v29
	v_mul_f32_e32 v29, 0xbfb8aa3b, v34
	v_exp_f32_e32 v29, v29
	v_mul_f32_e32 v31, 0xbfb8aa3b, v35
	v_exp_f32_e32 v31, v31
	v_lshlrev_b32_e32 v30, 16, v89
	v_add_f32_e32 v29, 1.0, v29
	v_rcp_f32_e32 v29, v29
	v_add_f32_e32 v31, 1.0, v31
	v_rcp_f32_e32 v31, v31
	v_mul_f32_e32 v30, v34, v30
	v_mul_f32_e32 v29, v29, v30
	v_and_b32_e32 v30, 0xffff0000, v89
	v_mul_f32_e32 v30, v35, v30
	v_mul_f32_e32 v30, v31, v30
	v_cvt_pk_bf16_f32 v29, v29, v30
	global_store_dwordx4 v[174:175], v[26:29], off offset:256
	v_pk_add_f32 v[24:25], v[24:25], v[76:77]
	v_pk_add_f32 v[14:15], v[14:15], v[74:75]
	v_pk_add_f32 v[26:27], v[20:21], v[72:73]
	v_pk_add_f32 v[20:21], v[18:19], v[70:71]
	v_mul_f32_e32 v18, 0xbfb8aa3b, v22
	v_exp_f32_e32 v18, v18
	v_mul_f32_e32 v28, 0xbfb8aa3b, v23
	v_exp_f32_e32 v28, v28
	v_lshlrev_b32_e32 v19, 16, v82
	v_add_f32_e32 v18, 1.0, v18
	v_rcp_f32_e32 v18, v18
	v_mul_f32_e32 v19, v22, v19
	v_add_f32_e32 v22, 1.0, v28
	v_rcp_f32_e32 v22, v22
	v_mul_f32_e32 v18, v18, v19
	v_and_b32_e32 v19, 0xffff0000, v82
	v_mul_f32_e32 v19, v23, v19
	v_mul_f32_e32 v19, v22, v19
	v_cvt_pk_bf16_f32 v18, v18, v19
	v_mul_f32_e32 v19, 0xbfb8aa3b, v24
	v_exp_f32_e32 v19, v19
	v_mul_f32_e32 v23, 0xbfb8aa3b, v25
	v_exp_f32_e32 v23, v23
	v_lshlrev_b32_e32 v22, 16, v83
	v_add_f32_e32 v19, 1.0, v19
	v_rcp_f32_e32 v19, v19
	v_add_f32_e32 v23, 1.0, v23
	v_rcp_f32_e32 v23, v23
	v_mul_f32_e32 v22, v24, v22
	v_mul_f32_e32 v19, v19, v22
	v_and_b32_e32 v22, 0xffff0000, v83
	v_mul_f32_e32 v22, v25, v22
	v_mul_f32_e32 v22, v23, v22
	v_cvt_pk_bf16_f32 v19, v19, v22
	v_mul_f32_e32 v22, 0xbfb8aa3b, v20
	v_exp_f32_e32 v22, v22
	v_mul_f32_e32 v24, 0xbfb8aa3b, v21
	v_exp_f32_e32 v24, v24
	v_lshlrev_b32_e32 v23, 16, v84
	v_add_f32_e32 v22, 1.0, v22
	v_rcp_f32_e32 v22, v22
	v_mul_f32_e32 v20, v20, v23
	v_add_f32_e32 v23, 1.0, v24
	v_rcp_f32_e32 v23, v23
	v_mul_f32_e32 v20, v22, v20
	v_and_b32_e32 v22, 0xffff0000, v84
	v_mul_f32_e32 v21, v21, v22
	v_mul_f32_e32 v21, v23, v21
	v_cvt_pk_bf16_f32 v20, v20, v21
	v_mul_f32_e32 v21, 0xbfb8aa3b, v26
	v_exp_f32_e32 v21, v21
	v_mul_f32_e32 v23, 0xbfb8aa3b, v27
	v_exp_f32_e32 v23, v23
	v_lshlrev_b32_e32 v22, 16, v85
	v_add_f32_e32 v21, 1.0, v21
	v_rcp_f32_e32 v21, v21
	v_add_f32_e32 v23, 1.0, v23
	v_rcp_f32_e32 v23, v23
	v_mul_f32_e32 v22, v26, v22
	v_mul_f32_e32 v21, v21, v22
	v_and_b32_e32 v22, 0xffff0000, v85
	v_mul_f32_e32 v22, v27, v22
	v_mul_f32_e32 v22, v23, v22
	v_cvt_pk_bf16_f32 v21, v21, v22
	global_store_dwordx4 v[172:173], v[18:21], off offset:256
	v_pk_add_f32 v[16:17], v[16:17], v[76:77]
	v_pk_add_f32 v[6:7], v[6:7], v[74:75]
	v_pk_add_f32 v[18:19], v[12:13], v[72:73]
	v_pk_add_f32 v[12:13], v[10:11], v[70:71]
	v_mul_f32_e32 v10, 0xbfb8aa3b, v14
	v_exp_f32_e32 v10, v10
	v_mul_f32_e32 v20, 0xbfb8aa3b, v15
	v_exp_f32_e32 v20, v20
	v_lshlrev_b32_e32 v11, 16, v78
	v_add_f32_e32 v10, 1.0, v10
	v_rcp_f32_e32 v10, v10
	v_mul_f32_e32 v11, v14, v11
	v_add_f32_e32 v14, 1.0, v20
	v_rcp_f32_e32 v14, v14
	v_mul_f32_e32 v10, v10, v11
	v_and_b32_e32 v11, 0xffff0000, v78
	v_mul_f32_e32 v11, v15, v11
	v_mul_f32_e32 v11, v14, v11
	v_cvt_pk_bf16_f32 v10, v10, v11
	v_mul_f32_e32 v11, 0xbfb8aa3b, v16
	v_exp_f32_e32 v11, v11
	v_mul_f32_e32 v15, 0xbfb8aa3b, v17
	v_exp_f32_e32 v15, v15
	v_lshlrev_b32_e32 v14, 16, v79
	v_add_f32_e32 v11, 1.0, v11
	v_rcp_f32_e32 v11, v11
	v_add_f32_e32 v15, 1.0, v15
	v_rcp_f32_e32 v15, v15
	v_mul_f32_e32 v14, v16, v14
	v_mul_f32_e32 v11, v11, v14
	v_and_b32_e32 v14, 0xffff0000, v79
	v_mul_f32_e32 v14, v17, v14
	v_mul_f32_e32 v14, v15, v14
	v_cvt_pk_bf16_f32 v11, v11, v14
	v_mul_f32_e32 v14, 0xbfb8aa3b, v12
	v_exp_f32_e32 v14, v14
	v_mul_f32_e32 v16, 0xbfb8aa3b, v13
	v_exp_f32_e32 v16, v16
	v_lshlrev_b32_e32 v15, 16, v80
	v_add_f32_e32 v14, 1.0, v14
	v_rcp_f32_e32 v14, v14
	v_mul_f32_e32 v12, v12, v15
	v_add_f32_e32 v15, 1.0, v16
	v_rcp_f32_e32 v15, v15
	v_mul_f32_e32 v12, v14, v12
	v_and_b32_e32 v14, 0xffff0000, v80
	v_mul_f32_e32 v13, v13, v14
	v_mul_f32_e32 v13, v15, v13
	v_cvt_pk_bf16_f32 v12, v12, v13
	v_mul_f32_e32 v13, 0xbfb8aa3b, v18
	v_exp_f32_e32 v13, v13
	v_mul_f32_e32 v15, 0xbfb8aa3b, v19
	v_exp_f32_e32 v15, v15
	v_lshlrev_b32_e32 v14, 16, v81
	v_add_f32_e32 v13, 1.0, v13
	v_rcp_f32_e32 v13, v13
	v_add_f32_e32 v15, 1.0, v15
	v_rcp_f32_e32 v15, v15
	v_mul_f32_e32 v14, v18, v14
	v_mul_f32_e32 v13, v13, v14
	v_and_b32_e32 v14, 0xffff0000, v81
	v_mul_f32_e32 v14, v19, v14
	v_mul_f32_e32 v14, v15, v14
	v_cvt_pk_bf16_f32 v13, v13, v14
	global_store_dwordx4 v[170:171], v[10:13], off offset:256
	v_pk_add_f32 v[8:9], v[8:9], v[76:77]
	s_nop 0
	v_pk_add_f32 v[10:11], v[4:5], v[72:73]
	v_pk_add_f32 v[4:5], v[2:3], v[70:71]
	v_mul_f32_e32 v2, 0xbfb8aa3b, v6
	v_exp_f32_e32 v2, v2
	v_mul_f32_e32 v12, 0xbfb8aa3b, v7
	v_exp_f32_e32 v12, v12
	v_lshlrev_b32_e32 v3, 16, v66
	v_add_f32_e32 v2, 1.0, v2
	v_rcp_f32_e32 v2, v2
	v_mul_f32_e32 v3, v6, v3
	v_add_f32_e32 v6, 1.0, v12
	v_rcp_f32_e32 v6, v6
	v_mul_f32_e32 v2, v2, v3
	v_and_b32_e32 v3, 0xffff0000, v66
	v_mul_f32_e32 v3, v7, v3
	v_mul_f32_e32 v3, v6, v3
	v_cvt_pk_bf16_f32 v2, v2, v3
	v_mul_f32_e32 v3, 0xbfb8aa3b, v8
	v_exp_f32_e32 v3, v3
	v_mul_f32_e32 v7, 0xbfb8aa3b, v9
	v_exp_f32_e32 v7, v7
	v_lshlrev_b32_e32 v6, 16, v67
	v_add_f32_e32 v3, 1.0, v3
	v_rcp_f32_e32 v3, v3
	v_add_f32_e32 v7, 1.0, v7
	v_rcp_f32_e32 v7, v7
	v_mul_f32_e32 v6, v8, v6
	v_mul_f32_e32 v3, v3, v6
	v_and_b32_e32 v6, 0xffff0000, v67
	v_mul_f32_e32 v6, v9, v6
	v_mul_f32_e32 v6, v7, v6
	v_cvt_pk_bf16_f32 v3, v3, v6
	v_mul_f32_e32 v6, 0xbfb8aa3b, v4
	v_exp_f32_e32 v6, v6
	v_mul_f32_e32 v8, 0xbfb8aa3b, v5
	v_exp_f32_e32 v8, v8
	v_lshlrev_b32_e32 v7, 16, v68
	v_add_f32_e32 v6, 1.0, v6
	v_rcp_f32_e32 v6, v6
	v_mul_f32_e32 v4, v4, v7
	v_add_f32_e32 v7, 1.0, v8
	v_rcp_f32_e32 v7, v7
	v_mul_f32_e32 v4, v6, v4
	v_and_b32_e32 v6, 0xffff0000, v68
	v_mul_f32_e32 v5, v5, v6
	v_mul_f32_e32 v5, v7, v5
	v_cvt_pk_bf16_f32 v4, v4, v5
	v_mul_f32_e32 v5, 0xbfb8aa3b, v10
	v_exp_f32_e32 v5, v5
	v_mul_f32_e32 v7, 0xbfb8aa3b, v11
	v_exp_f32_e32 v7, v7
	v_lshlrev_b32_e32 v6, 16, v69
	v_add_f32_e32 v5, 1.0, v5
	v_rcp_f32_e32 v5, v5
	v_add_f32_e32 v7, 1.0, v7
	v_rcp_f32_e32 v7, v7
	v_mul_f32_e32 v6, v10, v6
	v_mul_f32_e32 v5, v5, v6
	v_and_b32_e32 v6, 0xffff0000, v69
	v_mul_f32_e32 v6, v11, v6
	v_mul_f32_e32 v6, v7, v6
	v_cvt_pk_bf16_f32 v5, v5, v6
	global_store_dwordx4 v[168:169], v[2:5], off offset:256
	s_cbranch_vccnz .LBB0_1627
	s_andn2_b64 vcc, exec, s[20:21]
	s_cbranch_vccnz .LBB0_1626
	s_barrier
	s_branch .LBB0_1626
